# P2 c_q / c_kv norm epilogue: gain vectors loaded once per unit instead of per row block (16 serialised load+wait round trips removed)
# baseline (speedup 1.0000x reference)
;     __device__ __forceinline__ void operator()(const f32x4 (&acc)[2][2][4][2], const Unit& u, int wr, int wc, int fr, int fq) const {
;     ...
;         asm volatile("s_waitcnt lgkmcnt(0)" ::: "memory"); __builtin_amdgcn_s_barrier(); asm volatile("" ::: "memory");
;         const float invn = isq ? (1.0f / QL) : (1.0f / KVL);
;         const int c8 = wc * 32 + 8 * fq;
;         const float sgn = (fq < 2) ? -1.0f : 1.0f;
; #pragma unroll
;         for (int ai = 0; ai < 2; ++ai)
; #pragma unroll
;             for (int m = 0; m < 4; ++m) {
;                 const int rl = ai * HALF + wr * 64 + m * 16 + fr; const int row = u.pm * BM + rl;
;                 const float rs = rsqrtf(((P[rl * 4 + 0] + P[rl * 4 + 1]) + (P[rl * 4 + 2] + P[rl * 4 + 3])) * invn + EPS);
;                 if (isq) {
; #pragma unroll
;                     for (int bj = 0; bj < 2; ++bj) { const f32x4 g0 = *(const f32x4*)(gq + bj * HALF + c8), g1 = *(const f32x4*)(gq + bj * HALF + c8 + 4);
;                         const f32x4 v0 = acc[ai][bj][m][0] * rs * g0, v1 = acc[ai][bj][m][1] * rs * g1;
;                         u32x4 w; w.x = cvt_pk_bf16(v0[0], v0[1]); w.y = cvt_pk_bf16(v0[2], v0[3]); w.z = cvt_pk_bf16(v1[0], v1[1]); w.w = cvt_pk_bf16(v1[2], v1[3]);
;                         *(u32x4*)(CQNo + (size_t)row * QL + bj * HALF + c8) = w; }
;                 } else {
;                     { const f32x4 g0 = *(const f32x4*)(gkv + c8), g1 = *(const f32x4*)(gkv + c8 + 4);
;                       const f32x4 v0 = acc[ai][0][m][0] * rs * g0, v1 = acc[ai][0][m][1] * rs * g1;
;                       u32x4 w; w.x = cvt_pk_bf16(v0[0], v0[1]); w.y = cvt_pk_bf16(v0[2], v0[3]); w.z = cvt_pk_bf16(v1[0], v1[1]); w.w = cvt_pk_bf16(v1[2], v1[3]);
;                       *(u32x4*)(CKVNo + (size_t)row * KVL + c8) = w; }
;                     if (wc == 0) {
;                         f32x4 v0 = acc[ai][1][m][0], v1 = acc[ai][1][m][1];
;                         const float* rp = rope + (size_t)(row & (SEQ - 1)) * 32 + 16 * (fq & 1);
;                         const f32x4 c0 = *(const f32x4*)rp, c1 = *(const f32x4*)(rp + 4), c2 = *(const f32x4*)(rp + 8), c3 = *(const f32x4*)(rp + 12);
;                         const float cs[8] = {c0[0], c0[2], c1[0], c1[2], c2[0], c2[2], c3[0], c3[2]}, sn[8] = {c0[1], c0[3], c1[1], c1[3], c2[1], c2[3], c3[1], c3[3]};
; #pragma unroll
.LBB0_224:
	s_or_b64 exec, exec, s[10:11]
	v_add_u32_e32 v136, 0, v164
	s_waitcnt lgkmcnt(0)
	s_barrier
	s_cmp_lg_u64 s[12:13], 0
	s_cbranch_scc0 .Lp2n_q
	global_load_dwordx4 v[220:223], v[146:147], off
	global_load_dwordx4 v[224:227], v[146:147], off offset:16
	s_branch .Lp2n_j
.Lp2n_q:
	global_load_dwordx4 v[220:223], v[148:149], off
	global_load_dwordx4 v[224:227], v[148:149], off offset:16
	global_load_dwordx4 v[228:231], v[148:149], off offset:512
	global_load_dwordx4 v[240:243], v[148:149], off offset:528
.Lp2n_j:
	v_add_u32_e32 v136, 0x20400, v136
	ds_read_b128 v[184:187], v136
	v_cndmask_b32_e64 v159, v181, v194, s[8:9]
	s_lshl_b32 s18, s50, 8
	s_mov_b64 s[10:11], -1
	s_waitcnt lgkmcnt(0)
	v_mov_b32_e32 v160, v185
	v_mov_b32_e32 v161, v186
	v_mov_b32_e32 v185, v187
	v_pk_add_f32 v[160:161], v[160:161], v[184:185]
	s_nop 0
	v_add_f32_e32 v136, v160, v161
	v_fmaak_f32 v136, v159, v136, 0x358637bd
	v_mul_f32_e32 v158, 0x4b800000, v136
	v_cmp_gt_f32_e32 vcc, s68, v136
	v_add_u32_e32 v160, s18, v162
	v_ashrrev_i32_e32 v161, 31, v160
	v_cndmask_b32_e32 v136, v136, v158, vcc
	v_rsq_f32_e32 v136, v136
	s_nop 0
	v_mul_f32_e32 v158, 0x45800000, v136
	v_cndmask_b32_e32 v158, v136, v158, vcc
	v_cndmask_b32_e64 v136, 0, 1, s[38:39]
	s_and_b64 vcc, exec, s[12:13]
	v_cmp_ne_u32_e64 s[8:9], 1, v136
	s_cbranch_vccz .LBB0_228
	v_pk_mul_f32 v[192:193], v[126:127], v[158:159] op_sel_hi:[1,0]
	v_pk_mul_f32 v[196:197], v[124:125], v[158:159] op_sel_hi:[1,0]
	v_lshlrev_b64 v[202:203], 8, v[160:161]
	v_pk_mul_f32 v[198:199], v[122:123], v[158:159] op_sel_hi:[1,0]
	v_pk_mul_f32 v[200:201], v[120:121], v[158:159] op_sel_hi:[1,0]
	v_lshl_add_u64 v[202:203], v[140:141], 0, v[202:203]
	s_and_b64 vcc, exec, s[8:9]
	s_waitcnt vmcnt(0)
	v_pk_mul_f32 v[186:187], v[192:193], v[222:223]
	v_pk_mul_f32 v[184:185], v[196:197], v[220:221]
	v_pk_mul_f32 v[190:191], v[198:199], v[226:227]
	v_pk_mul_f32 v[188:189], v[200:201], v[224:225]
	v_cvt_pk_bf16_f32 v184, v184, v185
	v_cvt_pk_bf16_f32 v185, v186, v187
	s_nop 0
	v_cvt_pk_bf16_f32 v186, v188, v189
	v_cvt_pk_bf16_f32 v187, v190, v191
	global_store_dwordx4 v[202:203], v[184:187], off
	s_cbranch_vccnz .LBB0_227
	v_lshlrev_b32_e32 v136, 7, v160
	v_and_b32_e32 v136, 0x7e780, v136
	v_lshl_add_u64 v[192:193], v[142:143], 0, v[136:137]
	global_load_dwordx4 v[184:187], v[192:193], off
	global_load_dwordx4 v[188:191], v[192:193], off offset:32
	global_load_dwordx4 v[196:199], v[192:193], off offset:16
	global_load_dwordx4 v[200:203], v[192:193], off offset:48
	ds_bpermute_b32 v136, v183, v116
	ds_bpermute_b32 v182, v183, v112
	ds_bpermute_b32 v207, v183, v117
	ds_bpermute_b32 v209, v183, v113
	ds_bpermute_b32 v211, v183, v118
	ds_bpermute_b32 v213, v183, v114
	ds_bpermute_b32 v215, v183, v119
	ds_bpermute_b32 v217, v183, v115
	v_mov_b32_e32 v192, v116
	v_mov_b32_e32 v204, v112
	v_mov_b32_e32 v206, v117
	v_mov_b32_e32 v208, v113
	v_mov_b32_e32 v210, v118
	v_mov_b32_e32 v212, v114
	v_mov_b32_e32 v214, v119
	v_mov_b32_e32 v216, v115
	s_waitcnt lgkmcnt(7)
	v_mul_f32_e32 v193, v165, v136
	s_waitcnt lgkmcnt(6)
	v_mul_f32_e32 v205, v165, v182
	s_waitcnt lgkmcnt(5)
	v_mul_f32_e32 v207, v165, v207
	s_waitcnt lgkmcnt(4)
	v_mul_f32_e32 v209, v165, v209
	s_waitcnt lgkmcnt(3)
	v_mul_f32_e32 v211, v165, v211
	s_waitcnt lgkmcnt(2)
	v_mul_f32_e32 v213, v165, v213
	s_waitcnt lgkmcnt(1)
	v_mul_f32_e32 v215, v165, v215
	s_waitcnt lgkmcnt(0)
	v_mul_f32_e32 v217, v165, v217
	v_lshlrev_b64 v[218:219], 6, v[160:161]
	s_waitcnt vmcnt(3)
	v_pk_mul_f32 v[184:185], v[184:185], v[192:193]
	s_waitcnt vmcnt(2)
	v_pk_mul_f32 v[188:189], v[188:189], v[204:205]
	v_pk_mul_f32 v[186:187], v[186:187], v[206:207]
	v_pk_mul_f32 v[190:191], v[190:191], v[208:209]
	s_waitcnt vmcnt(1)
	v_pk_mul_f32 v[192:193], v[196:197], v[210:211]
	s_waitcnt vmcnt(0)
	v_pk_mul_f32 v[196:197], v[200:201], v[212:213]
	v_pk_mul_f32 v[198:199], v[198:199], v[214:215]
	v_pk_mul_f32 v[200:201], v[202:203], v[216:217]
	v_add_f32_e32 v136, v184, v185
	v_add_f32_e32 v182, v188, v189
	v_add_f32_e32 v184, v186, v187
	v_add_f32_e32 v186, v190, v191
	v_add_f32_e32 v185, v192, v193
	v_add_f32_e32 v187, v196, v197
	v_add_f32_e32 v188, v198, v199
	v_add_f32_e32 v189, v200, v201
	v_cvt_pk_bf16_f32 v184, v136, v184
	v_cvt_pk_bf16_f32 v185, v185, v188
	v_cvt_pk_bf16_f32 v186, v182, v186
	v_cvt_pk_bf16_f32 v187, v187, v189
	v_lshl_add_u64 v[188:189], v[144:145], 0, v[218:219]
	global_store_dwordx4 v[188:189], v[184:187], off

;     __device__ __forceinline__ void operator()(const f32x4 (&acc)[2][2][4][2], const Unit& u, int wr, int wc, int fr, int fq) const {
;     ...
;                 const int rl = ai * HALF + wr * 64 + m * 16 + fr; const int row = u.pm * BM + rl;
;                 const float rs = rsqrtf(((P[rl * 4 + 0] + P[rl * 4 + 1]) + (P[rl * 4 + 2] + P[rl * 4 + 3])) * invn + EPS);
;                 if (isq) {
; #pragma unroll
;                     for (int bj = 0; bj < 2; ++bj) { const f32x4 g0 = *(const f32x4*)(gq + bj * HALF + c8), g1 = *(const f32x4*)(gq + bj * HALF + c8 + 4);
;                         const f32x4 v0 = acc[ai][bj][m][0] * rs * g0, v1 = acc[ai][bj][m][1] * rs * g1;
;                         u32x4 w; w.x = cvt_pk_bf16(v0[0], v0[1]); w.y = cvt_pk_bf16(v0[2], v0[3]); w.z = cvt_pk_bf16(v1[0], v1[1]); w.w = cvt_pk_bf16(v1[2], v1[3]);
;                         *(u32x4*)(CQNo + (size_t)row * QL + bj * HALF + c8) = w; }
;                 } else {
;                     { const f32x4 g0 = *(const f32x4*)(gkv + c8), g1 = *(const f32x4*)(gkv + c8 + 4);
;                       const f32x4 v0 = acc[ai][0][m][0] * rs * g0, v1 = acc[ai][0][m][1] * rs * g1;
;                       u32x4 w; w.x = cvt_pk_bf16(v0[0], v0[1]); w.y = cvt_pk_bf16(v0[2], v0[3]); w.z = cvt_pk_bf16(v1[0], v1[1]); w.w = cvt_pk_bf16(v1[2], v1[3]);
;                       *(u32x4*)(CKVNo + (size_t)row * KVL + c8) = w; }
;                     if (wc == 0) {
;                         f32x4 v0 = acc[ai][1][m][0], v1 = acc[ai][1][m][1];
;                         const float* rp = rope + (size_t)(row & (SEQ - 1)) * 32 + 16 * (fq & 1);
;                         const f32x4 c0 = *(const f32x4*)rp, c1 = *(const f32x4*)(rp + 4), c2 = *(const f32x4*)(rp + 8), c3 = *(const f32x4*)(rp + 12);
;                         const float cs[8] = {c0[0], c0[2], c1[0], c1[2], c2[0], c2[2], c3[0], c3[2]}, sn[8] = {c0[1], c0[3], c1[1], c1[3], c2[1], c2[3], c3[1], c3[3]};
; #pragma unroll
;                         for (int e = 0; e < 4; ++e) { const float o0 = __shfl_xor(v0[e], 32), o1 = __shfl_xor(v1[e], 32);
;                             v0[e] = v0[e] * cs[e] + sgn * o0 * sn[e]; v1[e] = v1[e] * cs[4 + e] + sgn * o1 * sn[4 + e]; }
;                         u32x4 w; w.x = cvt_pk_bf16(v0[0], v0[1]); w.y = cvt_pk_bf16(v0[2], v0[3]); w.z = cvt_pk_bf16(v1[0], v1[1]); w.w = cvt_pk_bf16(v1[2], v1[3]);
.LBB0_228:
	s_andn2_b64 vcc, exec, s[10:11]
	s_cbranch_vccnz .LBB0_230
	v_lshlrev_b64 v[160:161], 9, v[160:161]
	v_pk_mul_f32 v[192:193], v[126:127], v[158:159] op_sel_hi:[1,0]
	v_pk_mul_f32 v[196:197], v[124:125], v[158:159] op_sel_hi:[1,0]
	v_pk_mul_f32 v[198:199], v[122:123], v[158:159] op_sel_hi:[1,0]
	v_pk_mul_f32 v[200:201], v[120:121], v[158:159] op_sel_hi:[1,0]
	v_lshl_add_u64 v[160:161], v[150:151], 0, v[160:161]
	s_waitcnt vmcnt(0)
	v_pk_mul_f32 v[186:187], v[192:193], v[222:223]
	v_pk_mul_f32 v[184:185], v[196:197], v[220:221]
	v_pk_mul_f32 v[190:191], v[198:199], v[226:227]
	v_pk_mul_f32 v[188:189], v[200:201], v[224:225]
	v_cvt_pk_bf16_f32 v184, v184, v185
	v_cvt_pk_bf16_f32 v185, v186, v187
	v_pk_mul_f32 v[192:193], v[118:119], v[158:159] op_sel_hi:[1,0]
	v_cvt_pk_bf16_f32 v186, v188, v189
	v_cvt_pk_bf16_f32 v187, v190, v191
	global_store_dwordx4 v[160:161], v[184:187], off
	s_nop 0
	v_pk_mul_f32 v[196:197], v[116:117], v[158:159] op_sel_hi:[1,0]
	v_pk_mul_f32 v[198:199], v[114:115], v[158:159] op_sel_hi:[1,0]
	v_pk_mul_f32 v[200:201], v[112:113], v[158:159] op_sel_hi:[1,0]
	v_pk_mul_f32 v[186:187], v[192:193], v[230:231]
	v_pk_mul_f32 v[184:185], v[196:197], v[228:229]
	v_pk_mul_f32 v[190:191], v[198:199], v[242:243]
	v_pk_mul_f32 v[188:189], v[200:201], v[240:241]
	v_cvt_pk_bf16_f32 v184, v184, v185
	v_cvt_pk_bf16_f32 v185, v186, v187
	s_nop 0
	v_cvt_pk_bf16_f32 v186, v188, v189
	v_cvt_pk_bf16_f32 v187, v190, v191
	global_store_dwordx4 v[160:161], v[184:187], off offset:256
.LBB0_230:
	ds_read_b128 v[184:187], v173
	v_add_u32_e32 v160, s18, v166
	s_mov_b64 s[52:53], -1
	v_ashrrev_i32_e32 v161, 31, v160
	s_waitcnt lgkmcnt(0)
	v_mov_b32_e32 v188, v185
	v_mov_b32_e32 v189, v186
	v_mov_b32_e32 v185, v187
	v_pk_add_f32 v[184:185], v[188:189], v[184:185]
	s_nop 0
	v_add_f32_e32 v136, v184, v185
	v_fmaak_f32 v136, v159, v136, 0x358637bd
	v_mul_f32_e32 v158, 0x4b800000, v136
	v_cmp_gt_f32_e32 vcc, s68, v136
	s_nop 1
	v_cndmask_b32_e32 v136, v136, v158, vcc
	v_rsq_f32_e32 v136, v136
	v_cndmask_b32_e64 v158, 0, 1, s[12:13]
	v_cmp_ne_u32_e64 s[10:11], 1, v158
	v_mul_f32_e32 v158, 0x45800000, v136
	v_cndmask_b32_e32 v158, v136, v158, vcc
	s_andn2_b64 vcc, exec, s[12:13]
	s_cbranch_vccnz .LBB0_234
	v_pk_mul_f32 v[192:193], v[110:111], v[158:159] op_sel_hi:[1,0]
	v_pk_mul_f32 v[196:197], v[108:109], v[158:159] op_sel_hi:[1,0]
	v_lshlrev_b64 v[202:203], 8, v[160:161]
	v_pk_mul_f32 v[198:199], v[106:107], v[158:159] op_sel_hi:[1,0]
	v_pk_mul_f32 v[200:201], v[104:105], v[158:159] op_sel_hi:[1,0]
	v_lshl_add_u64 v[202:203], v[140:141], 0, v[202:203]
	s_and_b64 vcc, exec, s[8:9]
	v_pk_mul_f32 v[186:187], v[192:193], v[222:223]
	v_pk_mul_f32 v[184:185], v[196:197], v[220:221]
	v_pk_mul_f32 v[190:191], v[198:199], v[226:227]
	v_pk_mul_f32 v[188:189], v[200:201], v[224:225]
	v_cvt_pk_bf16_f32 v184, v184, v185
	v_cvt_pk_bf16_f32 v185, v186, v187
	s_nop 0
	v_cvt_pk_bf16_f32 v186, v188, v189
	v_cvt_pk_bf16_f32 v187, v190, v191
	global_store_dwordx4 v[202:203], v[184:187], off
	s_cbranch_vccnz .LBB0_233
	v_lshlrev_b32_e32 v136, 7, v160
	v_and_b32_e32 v136, 0x7ef80, v136
	v_lshl_add_u64 v[192:193], v[142:143], 0, v[136:137]
	global_load_dwordx4 v[184:187], v[192:193], off
	global_load_dwordx4 v[188:191], v[192:193], off offset:32
	global_load_dwordx4 v[196:199], v[192:193], off offset:16
	global_load_dwordx4 v[200:203], v[192:193], off offset:48
	ds_bpermute_b32 v136, v183, v100
	ds_bpermute_b32 v182, v183, v96
	ds_bpermute_b32 v207, v183, v101
	ds_bpermute_b32 v209, v183, v97
	ds_bpermute_b32 v211, v183, v102
	ds_bpermute_b32 v213, v183, v98
	ds_bpermute_b32 v215, v183, v103
	ds_bpermute_b32 v217, v183, v99
	v_mov_b32_e32 v192, v100
	v_mov_b32_e32 v204, v96
	v_mov_b32_e32 v206, v101
	v_mov_b32_e32 v208, v97
	v_mov_b32_e32 v210, v102
	v_mov_b32_e32 v212, v98
	v_mov_b32_e32 v214, v103
	v_mov_b32_e32 v216, v99
	s_waitcnt lgkmcnt(7)
	v_mul_f32_e32 v193, v165, v136
	s_waitcnt lgkmcnt(6)
	v_mul_f32_e32 v205, v165, v182
	s_waitcnt lgkmcnt(5)
	v_mul_f32_e32 v207, v165, v207
	s_waitcnt lgkmcnt(4)
	v_mul_f32_e32 v209, v165, v209
	s_waitcnt lgkmcnt(3)
	v_mul_f32_e32 v211, v165, v211
	s_waitcnt lgkmcnt(2)
	v_mul_f32_e32 v213, v165, v213
	s_waitcnt lgkmcnt(1)
	v_mul_f32_e32 v215, v165, v215
	s_waitcnt lgkmcnt(0)
	v_mul_f32_e32 v217, v165, v217
	v_lshlrev_b64 v[218:219], 6, v[160:161]
	s_waitcnt vmcnt(3)
	v_pk_mul_f32 v[184:185], v[184:185], v[192:193]
	s_waitcnt vmcnt(2)
	v_pk_mul_f32 v[188:189], v[188:189], v[204:205]
	v_pk_mul_f32 v[186:187], v[186:187], v[206:207]
	v_pk_mul_f32 v[190:191], v[190:191], v[208:209]
	s_waitcnt vmcnt(1)
	v_pk_mul_f32 v[192:193], v[196:197], v[210:211]
	s_waitcnt vmcnt(0)
	v_pk_mul_f32 v[196:197], v[200:201], v[212:213]
	v_pk_mul_f32 v[198:199], v[198:199], v[214:215]
	v_pk_mul_f32 v[200:201], v[202:203], v[216:217]
	v_add_f32_e32 v136, v184, v185
	v_add_f32_e32 v182, v188, v189
	v_add_f32_e32 v184, v186, v187
	v_add_f32_e32 v186, v190, v191
	v_add_f32_e32 v185, v192, v193
	v_add_f32_e32 v187, v196, v197
	v_add_f32_e32 v188, v198, v199
	v_add_f32_e32 v189, v200, v201
	v_cvt_pk_bf16_f32 v184, v136, v184
	v_cvt_pk_bf16_f32 v185, v185, v188
	v_cvt_pk_bf16_f32 v186, v182, v186
	v_cvt_pk_bf16_f32 v187, v187, v189
	v_lshl_add_u64 v[188:189], v[144:145], 0, v[218:219]
	global_store_dwordx4 v[188:189], v[184:187], off

;     __device__ __forceinline__ void operator()(const f32x4 (&acc)[2][2][4][2], const Unit& u, int wr, int wc, int fr, int fq) const {
;     ...
;                 const int rl = ai * HALF + wr * 64 + m * 16 + fr; const int row = u.pm * BM + rl;
;                 const float rs = rsqrtf(((P[rl * 4 + 0] + P[rl * 4 + 1]) + (P[rl * 4 + 2] + P[rl * 4 + 3])) * invn + EPS);
;                 if (isq) {
; #pragma unroll
;                     for (int bj = 0; bj < 2; ++bj) { const f32x4 g0 = *(const f32x4*)(gq + bj * HALF + c8), g1 = *(const f32x4*)(gq + bj * HALF + c8 + 4);
;                         const f32x4 v0 = acc[ai][bj][m][0] * rs * g0, v1 = acc[ai][bj][m][1] * rs * g1;
;                         u32x4 w; w.x = cvt_pk_bf16(v0[0], v0[1]); w.y = cvt_pk_bf16(v0[2], v0[3]); w.z = cvt_pk_bf16(v1[0], v1[1]); w.w = cvt_pk_bf16(v1[2], v1[3]);
;                         *(u32x4*)(CQNo + (size_t)row * QL + bj * HALF + c8) = w; }
;                 } else {
;                     { const f32x4 g0 = *(const f32x4*)(gkv + c8), g1 = *(const f32x4*)(gkv + c8 + 4);
;                       const f32x4 v0 = acc[ai][0][m][0] * rs * g0, v1 = acc[ai][0][m][1] * rs * g1;
;                       u32x4 w; w.x = cvt_pk_bf16(v0[0], v0[1]); w.y = cvt_pk_bf16(v0[2], v0[3]); w.z = cvt_pk_bf16(v1[0], v1[1]); w.w = cvt_pk_bf16(v1[2], v1[3]);
;                       *(u32x4*)(CKVNo + (size_t)row * KVL + c8) = w; }
;                     if (wc == 0) {
;                         f32x4 v0 = acc[ai][1][m][0], v1 = acc[ai][1][m][1];
;                         const float* rp = rope + (size_t)(row & (SEQ - 1)) * 32 + 16 * (fq & 1);
;                         const f32x4 c0 = *(const f32x4*)rp, c1 = *(const f32x4*)(rp + 4), c2 = *(const f32x4*)(rp + 8), c3 = *(const f32x4*)(rp + 12);
;                         const float cs[8] = {c0[0], c0[2], c1[0], c1[2], c2[0], c2[2], c3[0], c3[2]}, sn[8] = {c0[1], c0[3], c1[1], c1[3], c2[1], c2[3], c3[1], c3[3]};
; #pragma unroll
;                         for (int e = 0; e < 4; ++e) { const float o0 = __shfl_xor(v0[e], 32), o1 = __shfl_xor(v1[e], 32);
;                             v0[e] = v0[e] * cs[e] + sgn * o0 * sn[e]; v1[e] = v1[e] * cs[4 + e] + sgn * o1 * sn[4 + e]; }
;                         u32x4 w; w.x = cvt_pk_bf16(v0[0], v0[1]); w.y = cvt_pk_bf16(v0[2], v0[3]); w.z = cvt_pk_bf16(v1[0], v1[1]); w.w = cvt_pk_bf16(v1[2], v1[3]);
.LBB0_234:
	s_andn2_b64 vcc, exec, s[52:53]
	s_cbranch_vccnz .LBB0_236
	v_lshlrev_b64 v[160:161], 9, v[160:161]
	v_pk_mul_f32 v[192:193], v[110:111], v[158:159] op_sel_hi:[1,0]
	v_pk_mul_f32 v[196:197], v[108:109], v[158:159] op_sel_hi:[1,0]
	v_pk_mul_f32 v[198:199], v[106:107], v[158:159] op_sel_hi:[1,0]
	v_pk_mul_f32 v[200:201], v[104:105], v[158:159] op_sel_hi:[1,0]
	v_lshl_add_u64 v[160:161], v[150:151], 0, v[160:161]
	v_pk_mul_f32 v[186:187], v[192:193], v[222:223]
	v_pk_mul_f32 v[184:185], v[196:197], v[220:221]
	v_pk_mul_f32 v[190:191], v[198:199], v[226:227]
	v_pk_mul_f32 v[188:189], v[200:201], v[224:225]
	v_cvt_pk_bf16_f32 v184, v184, v185
	v_cvt_pk_bf16_f32 v185, v186, v187
	v_pk_mul_f32 v[192:193], v[102:103], v[158:159] op_sel_hi:[1,0]
	v_cvt_pk_bf16_f32 v186, v188, v189
	v_cvt_pk_bf16_f32 v187, v190, v191
	global_store_dwordx4 v[160:161], v[184:187], off
	s_nop 0
	v_pk_mul_f32 v[196:197], v[100:101], v[158:159] op_sel_hi:[1,0]
	v_pk_mul_f32 v[198:199], v[98:99], v[158:159] op_sel_hi:[1,0]
	v_pk_mul_f32 v[200:201], v[96:97], v[158:159] op_sel_hi:[1,0]
	v_pk_mul_f32 v[186:187], v[192:193], v[230:231]
	v_pk_mul_f32 v[184:185], v[196:197], v[228:229]
	v_pk_mul_f32 v[190:191], v[198:199], v[242:243]
	v_pk_mul_f32 v[188:189], v[200:201], v[240:241]
	v_cvt_pk_bf16_f32 v184, v184, v185
	v_cvt_pk_bf16_f32 v185, v186, v187
	s_nop 0
	v_cvt_pk_bf16_f32 v186, v188, v189
	v_cvt_pk_bf16_f32 v187, v190, v191
	global_store_dwordx4 v[160:161], v[184:187], off offset:256
.LBB0_236:
	ds_read_b128 v[184:187], v174
	s_mov_b64 s[52:53], -1
	s_and_b64 vcc, exec, s[10:11]
	s_waitcnt lgkmcnt(0)
	v_mov_b32_e32 v160, v185
	v_mov_b32_e32 v161, v186
	v_mov_b32_e32 v185, v187
	v_pk_add_f32 v[160:161], v[160:161], v[184:185]
	s_nop 0
	v_add_f32_e32 v136, v160, v161
	v_fmaak_f32 v136, v159, v136, 0x358637bd
	v_mul_f32_e32 v158, 0x4b800000, v136
	v_cmp_gt_f32_e64 s[12:13], s68, v136
	v_add_u32_e32 v160, s18, v167
	v_ashrrev_i32_e32 v161, 31, v160
	v_cndmask_b32_e64 v136, v136, v158, s[12:13]
	v_rsq_f32_e32 v136, v136
	s_nop 0
	v_mul_f32_e32 v158, 0x45800000, v136
	v_cndmask_b32_e64 v158, v136, v158, s[12:13]
	s_cbranch_vccnz .LBB0_240
	v_pk_mul_f32 v[192:193], v[94:95], v[158:159] op_sel_hi:[1,0]
	v_pk_mul_f32 v[196:197], v[92:93], v[158:159] op_sel_hi:[1,0]
	v_lshlrev_b64 v[202:203], 8, v[160:161]
	v_pk_mul_f32 v[198:199], v[90:91], v[158:159] op_sel_hi:[1,0]
	v_pk_mul_f32 v[200:201], v[88:89], v[158:159] op_sel_hi:[1,0]
	v_lshl_add_u64 v[202:203], v[140:141], 0, v[202:203]
	s_and_b64 vcc, exec, s[8:9]
	v_pk_mul_f32 v[186:187], v[192:193], v[222:223]
	v_pk_mul_f32 v[184:185], v[196:197], v[220:221]
	v_pk_mul_f32 v[190:191], v[198:199], v[226:227]
	v_pk_mul_f32 v[188:189], v[200:201], v[224:225]
	v_cvt_pk_bf16_f32 v184, v184, v185
	v_cvt_pk_bf16_f32 v185, v186, v187
	s_nop 0
	v_cvt_pk_bf16_f32 v186, v188, v189
	v_cvt_pk_bf16_f32 v187, v190, v191
	global_store_dwordx4 v[202:203], v[184:187], off
	s_cbranch_vccnz .LBB0_239
	v_lshlrev_b32_e32 v136, 7, v160
	v_and_b32_e32 v136, 0x7f780, v136
	v_lshl_add_u64 v[192:193], v[142:143], 0, v[136:137]
	global_load_dwordx4 v[184:187], v[192:193], off
	global_load_dwordx4 v[188:191], v[192:193], off offset:32
	global_load_dwordx4 v[196:199], v[192:193], off offset:16
	global_load_dwordx4 v[200:203], v[192:193], off offset:48
	ds_bpermute_b32 v136, v183, v84
	ds_bpermute_b32 v182, v183, v80
	ds_bpermute_b32 v207, v183, v85
	ds_bpermute_b32 v209, v183, v81
	ds_bpermute_b32 v211, v183, v86
	ds_bpermute_b32 v213, v183, v82
	ds_bpermute_b32 v215, v183, v87
	ds_bpermute_b32 v217, v183, v83
	v_mov_b32_e32 v192, v84
	v_mov_b32_e32 v204, v80
	v_mov_b32_e32 v206, v85
	v_mov_b32_e32 v208, v81
	v_mov_b32_e32 v210, v86
	v_mov_b32_e32 v212, v82
	v_mov_b32_e32 v214, v87
	v_mov_b32_e32 v216, v83
	s_waitcnt lgkmcnt(7)
	v_mul_f32_e32 v193, v165, v136
	s_waitcnt lgkmcnt(6)
	v_mul_f32_e32 v205, v165, v182
	s_waitcnt lgkmcnt(5)
	v_mul_f32_e32 v207, v165, v207
	s_waitcnt lgkmcnt(4)
	v_mul_f32_e32 v209, v165, v209
	s_waitcnt lgkmcnt(3)
	v_mul_f32_e32 v211, v165, v211
	s_waitcnt lgkmcnt(2)
	v_mul_f32_e32 v213, v165, v213
	s_waitcnt lgkmcnt(1)
	v_mul_f32_e32 v215, v165, v215
	s_waitcnt lgkmcnt(0)
	v_mul_f32_e32 v217, v165, v217
	v_lshlrev_b64 v[218:219], 6, v[160:161]
	s_waitcnt vmcnt(3)
	v_pk_mul_f32 v[184:185], v[184:185], v[192:193]
	s_waitcnt vmcnt(2)
	v_pk_mul_f32 v[188:189], v[188:189], v[204:205]
	v_pk_mul_f32 v[186:187], v[186:187], v[206:207]
	v_pk_mul_f32 v[190:191], v[190:191], v[208:209]
	s_waitcnt vmcnt(1)
	v_pk_mul_f32 v[192:193], v[196:197], v[210:211]
	s_waitcnt vmcnt(0)
	v_pk_mul_f32 v[196:197], v[200:201], v[212:213]
	v_pk_mul_f32 v[198:199], v[198:199], v[214:215]
	v_pk_mul_f32 v[200:201], v[202:203], v[216:217]
	v_add_f32_e32 v136, v184, v185
	v_add_f32_e32 v182, v188, v189
	v_add_f32_e32 v184, v186, v187
	v_add_f32_e32 v186, v190, v191
	v_add_f32_e32 v185, v192, v193
	v_add_f32_e32 v187, v196, v197
	v_add_f32_e32 v188, v198, v199
	v_add_f32_e32 v189, v200, v201
	v_cvt_pk_bf16_f32 v184, v136, v184
	v_cvt_pk_bf16_f32 v185, v185, v188
	v_cvt_pk_bf16_f32 v186, v182, v186
	v_cvt_pk_bf16_f32 v187, v187, v189
	v_lshl_add_u64 v[188:189], v[144:145], 0, v[218:219]
	global_store_dwordx4 v[188:189], v[184:187], off

;     __device__ __forceinline__ void operator()(const f32x4 (&acc)[2][2][4][2], const Unit& u, int wr, int wc, int fr, int fq) const {
;     ...
;                 const int rl = ai * HALF + wr * 64 + m * 16 + fr; const int row = u.pm * BM + rl;
;                 const float rs = rsqrtf(((P[rl * 4 + 0] + P[rl * 4 + 1]) + (P[rl * 4 + 2] + P[rl * 4 + 3])) * invn + EPS);
;                 if (isq) {
; #pragma unroll
;                     for (int bj = 0; bj < 2; ++bj) { const f32x4 g0 = *(const f32x4*)(gq + bj * HALF + c8), g1 = *(const f32x4*)(gq + bj * HALF + c8 + 4);
;                         const f32x4 v0 = acc[ai][bj][m][0] * rs * g0, v1 = acc[ai][bj][m][1] * rs * g1;
;                         u32x4 w; w.x = cvt_pk_bf16(v0[0], v0[1]); w.y = cvt_pk_bf16(v0[2], v0[3]); w.z = cvt_pk_bf16(v1[0], v1[1]); w.w = cvt_pk_bf16(v1[2], v1[3]);
;                         *(u32x4*)(CQNo + (size_t)row * QL + bj * HALF + c8) = w; }
;                 } else {
;                     { const f32x4 g0 = *(const f32x4*)(gkv + c8), g1 = *(const f32x4*)(gkv + c8 + 4);
;                       const f32x4 v0 = acc[ai][0][m][0] * rs * g0, v1 = acc[ai][0][m][1] * rs * g1;
;                       u32x4 w; w.x = cvt_pk_bf16(v0[0], v0[1]); w.y = cvt_pk_bf16(v0[2], v0[3]); w.z = cvt_pk_bf16(v1[0], v1[1]); w.w = cvt_pk_bf16(v1[2], v1[3]);
;                       *(u32x4*)(CKVNo + (size_t)row * KVL + c8) = w; }
;                     if (wc == 0) {
;                         f32x4 v0 = acc[ai][1][m][0], v1 = acc[ai][1][m][1];
;                         const float* rp = rope + (size_t)(row & (SEQ - 1)) * 32 + 16 * (fq & 1);
;                         const f32x4 c0 = *(const f32x4*)rp, c1 = *(const f32x4*)(rp + 4), c2 = *(const f32x4*)(rp + 8), c3 = *(const f32x4*)(rp + 12);
;                         const float cs[8] = {c0[0], c0[2], c1[0], c1[2], c2[0], c2[2], c3[0], c3[2]}, sn[8] = {c0[1], c0[3], c1[1], c1[3], c2[1], c2[3], c3[1], c3[3]};
; #pragma unroll
;                         for (int e = 0; e < 4; ++e) { const float o0 = __shfl_xor(v0[e], 32), o1 = __shfl_xor(v1[e], 32);
;                             v0[e] = v0[e] * cs[e] + sgn * o0 * sn[e]; v1[e] = v1[e] * cs[4 + e] + sgn * o1 * sn[4 + e]; }
;                         u32x4 w; w.x = cvt_pk_bf16(v0[0], v0[1]); w.y = cvt_pk_bf16(v0[2], v0[3]); w.z = cvt_pk_bf16(v1[0], v1[1]); w.w = cvt_pk_bf16(v1[2], v1[3]);
.LBB0_240:
	s_andn2_b64 vcc, exec, s[52:53]
	s_cbranch_vccnz .LBB0_242
	v_lshlrev_b64 v[160:161], 9, v[160:161]
	v_pk_mul_f32 v[192:193], v[94:95], v[158:159] op_sel_hi:[1,0]
	v_pk_mul_f32 v[196:197], v[92:93], v[158:159] op_sel_hi:[1,0]
	v_pk_mul_f32 v[198:199], v[90:91], v[158:159] op_sel_hi:[1,0]
	v_pk_mul_f32 v[200:201], v[88:89], v[158:159] op_sel_hi:[1,0]
	v_lshl_add_u64 v[160:161], v[150:151], 0, v[160:161]
	v_pk_mul_f32 v[186:187], v[192:193], v[222:223]
	v_pk_mul_f32 v[184:185], v[196:197], v[220:221]
	v_pk_mul_f32 v[190:191], v[198:199], v[226:227]
	v_pk_mul_f32 v[188:189], v[200:201], v[224:225]
	v_cvt_pk_bf16_f32 v184, v184, v185
	v_cvt_pk_bf16_f32 v185, v186, v187
	v_pk_mul_f32 v[192:193], v[86:87], v[158:159] op_sel_hi:[1,0]
	v_cvt_pk_bf16_f32 v186, v188, v189
	v_cvt_pk_bf16_f32 v187, v190, v191
	global_store_dwordx4 v[160:161], v[184:187], off
	s_nop 0
	v_pk_mul_f32 v[196:197], v[84:85], v[158:159] op_sel_hi:[1,0]
	v_pk_mul_f32 v[198:199], v[82:83], v[158:159] op_sel_hi:[1,0]
	v_pk_mul_f32 v[200:201], v[80:81], v[158:159] op_sel_hi:[1,0]
	v_pk_mul_f32 v[186:187], v[192:193], v[230:231]
	v_pk_mul_f32 v[184:185], v[196:197], v[228:229]
	v_pk_mul_f32 v[190:191], v[198:199], v[242:243]
	v_pk_mul_f32 v[188:189], v[200:201], v[240:241]
	v_cvt_pk_bf16_f32 v184, v184, v185
	v_cvt_pk_bf16_f32 v185, v186, v187
	s_nop 0
	v_cvt_pk_bf16_f32 v186, v188, v189
	v_cvt_pk_bf16_f32 v187, v190, v191
	global_store_dwordx4 v[160:161], v[184:187], off offset:256
.LBB0_242:
	ds_read_b128 v[184:187], v175
	s_mov_b64 s[52:53], -1
	s_and_b64 vcc, exec, s[10:11]
	s_waitcnt lgkmcnt(0)
	v_mov_b32_e32 v160, v185
	v_mov_b32_e32 v161, v186
	v_mov_b32_e32 v185, v187
	v_pk_add_f32 v[160:161], v[160:161], v[184:185]
	s_nop 0
	v_add_f32_e32 v136, v160, v161
	v_fmaak_f32 v136, v159, v136, 0x358637bd
	v_mul_f32_e32 v158, 0x4b800000, v136
	v_cmp_gt_f32_e64 s[12:13], s68, v136
	v_add_u32_e32 v160, s18, v168
	v_ashrrev_i32_e32 v161, 31, v160
	v_cndmask_b32_e64 v136, v136, v158, s[12:13]
	v_rsq_f32_e32 v136, v136
	s_nop 0
	v_mul_f32_e32 v158, 0x45800000, v136
	v_cndmask_b32_e64 v158, v136, v158, s[12:13]
	s_cbranch_vccnz .LBB0_246
	v_pk_mul_f32 v[192:193], v[78:79], v[158:159] op_sel_hi:[1,0]
	v_pk_mul_f32 v[196:197], v[76:77], v[158:159] op_sel_hi:[1,0]
	v_lshlrev_b64 v[202:203], 8, v[160:161]
	v_pk_mul_f32 v[198:199], v[74:75], v[158:159] op_sel_hi:[1,0]
	v_pk_mul_f32 v[200:201], v[72:73], v[158:159] op_sel_hi:[1,0]
	v_lshl_add_u64 v[202:203], v[140:141], 0, v[202:203]
	s_and_b64 vcc, exec, s[8:9]
	v_pk_mul_f32 v[186:187], v[192:193], v[222:223]
	v_pk_mul_f32 v[184:185], v[196:197], v[220:221]
	v_pk_mul_f32 v[190:191], v[198:199], v[226:227]
	v_pk_mul_f32 v[188:189], v[200:201], v[224:225]
	v_cvt_pk_bf16_f32 v184, v184, v185
	v_cvt_pk_bf16_f32 v185, v186, v187
	s_nop 0
	v_cvt_pk_bf16_f32 v186, v188, v189
	v_cvt_pk_bf16_f32 v187, v190, v191
	global_store_dwordx4 v[202:203], v[184:187], off
	s_cbranch_vccnz .LBB0_245
	v_lshlrev_b32_e32 v136, 7, v160
	v_and_b32_e32 v136, 0x7ff80, v136
	v_lshl_add_u64 v[192:193], v[142:143], 0, v[136:137]
	global_load_dwordx4 v[184:187], v[192:193], off
	global_load_dwordx4 v[188:191], v[192:193], off offset:32
	global_load_dwordx4 v[196:199], v[192:193], off offset:16
	global_load_dwordx4 v[200:203], v[192:193], off offset:48
	ds_bpermute_b32 v136, v183, v68
	ds_bpermute_b32 v182, v183, v64
	ds_bpermute_b32 v207, v183, v69
	ds_bpermute_b32 v209, v183, v65
	ds_bpermute_b32 v211, v183, v70
	ds_bpermute_b32 v213, v183, v66
	ds_bpermute_b32 v215, v183, v71
	ds_bpermute_b32 v217, v183, v67
	v_mov_b32_e32 v192, v68
	v_mov_b32_e32 v204, v64
	v_mov_b32_e32 v206, v69
	v_mov_b32_e32 v208, v65
	v_mov_b32_e32 v210, v70
	v_mov_b32_e32 v212, v66
	v_mov_b32_e32 v214, v71
	v_mov_b32_e32 v216, v67
	s_waitcnt lgkmcnt(7)
	v_mul_f32_e32 v193, v165, v136
	s_waitcnt lgkmcnt(6)
	v_mul_f32_e32 v205, v165, v182
	s_waitcnt lgkmcnt(5)
	v_mul_f32_e32 v207, v165, v207
	s_waitcnt lgkmcnt(4)
	v_mul_f32_e32 v209, v165, v209
	s_waitcnt lgkmcnt(3)
	v_mul_f32_e32 v211, v165, v211
	s_waitcnt lgkmcnt(2)
	v_mul_f32_e32 v213, v165, v213
	s_waitcnt lgkmcnt(1)
	v_mul_f32_e32 v215, v165, v215
	s_waitcnt lgkmcnt(0)
	v_mul_f32_e32 v217, v165, v217
	v_lshlrev_b64 v[218:219], 6, v[160:161]
	s_waitcnt vmcnt(3)
	v_pk_mul_f32 v[184:185], v[184:185], v[192:193]
	s_waitcnt vmcnt(2)
	v_pk_mul_f32 v[188:189], v[188:189], v[204:205]
	v_pk_mul_f32 v[186:187], v[186:187], v[206:207]
	v_pk_mul_f32 v[190:191], v[190:191], v[208:209]
	s_waitcnt vmcnt(1)
	v_pk_mul_f32 v[192:193], v[196:197], v[210:211]
	s_waitcnt vmcnt(0)
	v_pk_mul_f32 v[196:197], v[200:201], v[212:213]
	v_pk_mul_f32 v[198:199], v[198:199], v[214:215]
	v_pk_mul_f32 v[200:201], v[202:203], v[216:217]
	v_add_f32_e32 v136, v184, v185
	v_add_f32_e32 v182, v188, v189
	v_add_f32_e32 v184, v186, v187
	v_add_f32_e32 v186, v190, v191
	v_add_f32_e32 v185, v192, v193
	v_add_f32_e32 v187, v196, v197
	v_add_f32_e32 v188, v198, v199
	v_add_f32_e32 v189, v200, v201
	v_cvt_pk_bf16_f32 v184, v136, v184
	v_cvt_pk_bf16_f32 v185, v185, v188
	v_cvt_pk_bf16_f32 v186, v182, v186
	v_cvt_pk_bf16_f32 v187, v187, v189
	v_lshl_add_u64 v[188:189], v[144:145], 0, v[218:219]
	global_store_dwordx4 v[188:189], v[184:187], off

;     __device__ __forceinline__ void operator()(const f32x4 (&acc)[2][2][4][2], const Unit& u, int wr, int wc, int fr, int fq) const {
;     ...
;                 const int rl = ai * HALF + wr * 64 + m * 16 + fr; const int row = u.pm * BM + rl;
;                 const float rs = rsqrtf(((P[rl * 4 + 0] + P[rl * 4 + 1]) + (P[rl * 4 + 2] + P[rl * 4 + 3])) * invn + EPS);
;                 if (isq) {
; #pragma unroll
;                     for (int bj = 0; bj < 2; ++bj) { const f32x4 g0 = *(const f32x4*)(gq + bj * HALF + c8), g1 = *(const f32x4*)(gq + bj * HALF + c8 + 4);
;                         const f32x4 v0 = acc[ai][bj][m][0] * rs * g0, v1 = acc[ai][bj][m][1] * rs * g1;
;                         u32x4 w; w.x = cvt_pk_bf16(v0[0], v0[1]); w.y = cvt_pk_bf16(v0[2], v0[3]); w.z = cvt_pk_bf16(v1[0], v1[1]); w.w = cvt_pk_bf16(v1[2], v1[3]);
;                         *(u32x4*)(CQNo + (size_t)row * QL + bj * HALF + c8) = w; }
;                 } else {
;                     { const f32x4 g0 = *(const f32x4*)(gkv + c8), g1 = *(const f32x4*)(gkv + c8 + 4);
;                       const f32x4 v0 = acc[ai][0][m][0] * rs * g0, v1 = acc[ai][0][m][1] * rs * g1;
;                       u32x4 w; w.x = cvt_pk_bf16(v0[0], v0[1]); w.y = cvt_pk_bf16(v0[2], v0[3]); w.z = cvt_pk_bf16(v1[0], v1[1]); w.w = cvt_pk_bf16(v1[2], v1[3]);
;                       *(u32x4*)(CKVNo + (size_t)row * KVL + c8) = w; }
;                     if (wc == 0) {
;                         f32x4 v0 = acc[ai][1][m][0], v1 = acc[ai][1][m][1];
;                         const float* rp = rope + (size_t)(row & (SEQ - 1)) * 32 + 16 * (fq & 1);
;                         const f32x4 c0 = *(const f32x4*)rp, c1 = *(const f32x4*)(rp + 4), c2 = *(const f32x4*)(rp + 8), c3 = *(const f32x4*)(rp + 12);
;                         const float cs[8] = {c0[0], c0[2], c1[0], c1[2], c2[0], c2[2], c3[0], c3[2]}, sn[8] = {c0[1], c0[3], c1[1], c1[3], c2[1], c2[3], c3[1], c3[3]};
; #pragma unroll
;                         for (int e = 0; e < 4; ++e) { const float o0 = __shfl_xor(v0[e], 32), o1 = __shfl_xor(v1[e], 32);
;                             v0[e] = v0[e] * cs[e] + sgn * o0 * sn[e]; v1[e] = v1[e] * cs[4 + e] + sgn * o1 * sn[4 + e]; }
;                         u32x4 w; w.x = cvt_pk_bf16(v0[0], v0[1]); w.y = cvt_pk_bf16(v0[2], v0[3]); w.z = cvt_pk_bf16(v1[0], v1[1]); w.w = cvt_pk_bf16(v1[2], v1[3]);
.LBB0_246:
	s_andn2_b64 vcc, exec, s[52:53]
	s_cbranch_vccnz .LBB0_248
	v_lshlrev_b64 v[160:161], 9, v[160:161]
	v_pk_mul_f32 v[192:193], v[78:79], v[158:159] op_sel_hi:[1,0]
	v_pk_mul_f32 v[196:197], v[76:77], v[158:159] op_sel_hi:[1,0]
	v_pk_mul_f32 v[198:199], v[74:75], v[158:159] op_sel_hi:[1,0]
	v_pk_mul_f32 v[200:201], v[72:73], v[158:159] op_sel_hi:[1,0]
	v_lshl_add_u64 v[160:161], v[150:151], 0, v[160:161]
	v_pk_mul_f32 v[186:187], v[192:193], v[222:223]
	v_pk_mul_f32 v[184:185], v[196:197], v[220:221]
	v_pk_mul_f32 v[190:191], v[198:199], v[226:227]
	v_pk_mul_f32 v[188:189], v[200:201], v[224:225]
	v_cvt_pk_bf16_f32 v184, v184, v185
	v_cvt_pk_bf16_f32 v185, v186, v187
	v_pk_mul_f32 v[192:193], v[70:71], v[158:159] op_sel_hi:[1,0]
	v_cvt_pk_bf16_f32 v186, v188, v189
	v_cvt_pk_bf16_f32 v187, v190, v191
	global_store_dwordx4 v[160:161], v[184:187], off
	s_nop 0
	v_pk_mul_f32 v[196:197], v[68:69], v[158:159] op_sel_hi:[1,0]
	v_pk_mul_f32 v[198:199], v[66:67], v[158:159] op_sel_hi:[1,0]
	v_pk_mul_f32 v[200:201], v[64:65], v[158:159] op_sel_hi:[1,0]
	v_pk_mul_f32 v[186:187], v[192:193], v[230:231]
	v_pk_mul_f32 v[184:185], v[196:197], v[228:229]
	v_pk_mul_f32 v[190:191], v[198:199], v[242:243]
	v_pk_mul_f32 v[188:189], v[200:201], v[240:241]
	v_cvt_pk_bf16_f32 v184, v184, v185
	v_cvt_pk_bf16_f32 v185, v186, v187
	s_nop 0
	v_cvt_pk_bf16_f32 v186, v188, v189
	v_cvt_pk_bf16_f32 v187, v190, v191
	global_store_dwordx4 v[160:161], v[184:187], off offset:256
.LBB0_248:
	ds_read_b128 v[184:187], v176
	s_mov_b64 s[52:53], -1
	s_and_b64 vcc, exec, s[10:11]
	s_waitcnt lgkmcnt(0)
	v_mov_b32_e32 v160, v185
	v_mov_b32_e32 v161, v186
	v_mov_b32_e32 v185, v187
	v_pk_add_f32 v[160:161], v[160:161], v[184:185]
	s_nop 0
	v_add_f32_e32 v136, v160, v161
	v_fmaak_f32 v136, v159, v136, 0x358637bd
	v_mul_f32_e32 v158, 0x4b800000, v136
	v_cmp_gt_f32_e64 s[12:13], s68, v136
	v_add_u32_e32 v160, s18, v169
	v_ashrrev_i32_e32 v161, 31, v160
	v_cndmask_b32_e64 v136, v136, v158, s[12:13]
	v_rsq_f32_e32 v136, v136
	s_nop 0
	v_mul_f32_e32 v158, 0x45800000, v136
	v_cndmask_b32_e64 v158, v136, v158, s[12:13]
	s_cbranch_vccnz .LBB0_252
	v_pk_mul_f32 v[192:193], v[62:63], v[158:159] op_sel_hi:[1,0]
	v_pk_mul_f32 v[196:197], v[60:61], v[158:159] op_sel_hi:[1,0]
	v_lshlrev_b64 v[202:203], 8, v[160:161]
	v_pk_mul_f32 v[198:199], v[58:59], v[158:159] op_sel_hi:[1,0]
	v_pk_mul_f32 v[200:201], v[56:57], v[158:159] op_sel_hi:[1,0]
	v_lshl_add_u64 v[202:203], v[140:141], 0, v[202:203]
	s_and_b64 vcc, exec, s[8:9]
	v_pk_mul_f32 v[186:187], v[192:193], v[222:223]
	v_pk_mul_f32 v[184:185], v[196:197], v[220:221]
	v_pk_mul_f32 v[190:191], v[198:199], v[226:227]
	v_pk_mul_f32 v[188:189], v[200:201], v[224:225]
	v_cvt_pk_bf16_f32 v184, v184, v185
	v_cvt_pk_bf16_f32 v185, v186, v187
	s_nop 0
	v_cvt_pk_bf16_f32 v186, v188, v189
	v_cvt_pk_bf16_f32 v187, v190, v191
	global_store_dwordx4 v[202:203], v[184:187], off
	s_cbranch_vccnz .LBB0_251
	v_lshlrev_b32_e32 v136, 7, v160
	v_and_b32_e32 v136, 0x7e780, v136
	v_lshl_add_u64 v[192:193], v[142:143], 0, v[136:137]
	global_load_dwordx4 v[184:187], v[192:193], off
	global_load_dwordx4 v[188:191], v[192:193], off offset:32
	global_load_dwordx4 v[196:199], v[192:193], off offset:16
	global_load_dwordx4 v[200:203], v[192:193], off offset:48
	ds_bpermute_b32 v136, v183, v52
	ds_bpermute_b32 v182, v183, v48
	ds_bpermute_b32 v207, v183, v53
	ds_bpermute_b32 v209, v183, v49
	ds_bpermute_b32 v211, v183, v54
	ds_bpermute_b32 v213, v183, v50
	ds_bpermute_b32 v215, v183, v55
	ds_bpermute_b32 v217, v183, v51
	v_mov_b32_e32 v192, v52
	v_mov_b32_e32 v204, v48
	v_mov_b32_e32 v206, v53
	v_mov_b32_e32 v208, v49
	v_mov_b32_e32 v210, v54
	v_mov_b32_e32 v212, v50
	v_mov_b32_e32 v214, v55
	v_mov_b32_e32 v216, v51
	s_waitcnt lgkmcnt(7)
	v_mul_f32_e32 v193, v165, v136
	s_waitcnt lgkmcnt(6)
	v_mul_f32_e32 v205, v165, v182
	s_waitcnt lgkmcnt(5)
	v_mul_f32_e32 v207, v165, v207
	s_waitcnt lgkmcnt(4)
	v_mul_f32_e32 v209, v165, v209
	s_waitcnt lgkmcnt(3)
	v_mul_f32_e32 v211, v165, v211
	s_waitcnt lgkmcnt(2)
	v_mul_f32_e32 v213, v165, v213
	s_waitcnt lgkmcnt(1)
	v_mul_f32_e32 v215, v165, v215
	s_waitcnt lgkmcnt(0)
	v_mul_f32_e32 v217, v165, v217
	v_lshlrev_b64 v[218:219], 6, v[160:161]
	s_waitcnt vmcnt(3)
	v_pk_mul_f32 v[184:185], v[184:185], v[192:193]
	s_waitcnt vmcnt(2)
	v_pk_mul_f32 v[188:189], v[188:189], v[204:205]
	v_pk_mul_f32 v[186:187], v[186:187], v[206:207]
	v_pk_mul_f32 v[190:191], v[190:191], v[208:209]
	s_waitcnt vmcnt(1)
	v_pk_mul_f32 v[192:193], v[196:197], v[210:211]
	s_waitcnt vmcnt(0)
	v_pk_mul_f32 v[196:197], v[200:201], v[212:213]
	v_pk_mul_f32 v[198:199], v[198:199], v[214:215]
	v_pk_mul_f32 v[200:201], v[202:203], v[216:217]
	v_add_f32_e32 v136, v184, v185
	v_add_f32_e32 v182, v188, v189
	v_add_f32_e32 v184, v186, v187
	v_add_f32_e32 v186, v190, v191
	v_add_f32_e32 v185, v192, v193
	v_add_f32_e32 v187, v196, v197
	v_add_f32_e32 v188, v198, v199
	v_add_f32_e32 v189, v200, v201
	v_cvt_pk_bf16_f32 v184, v136, v184
	v_cvt_pk_bf16_f32 v185, v185, v188
	v_cvt_pk_bf16_f32 v186, v182, v186
	v_cvt_pk_bf16_f32 v187, v187, v189
	v_lshl_add_u64 v[188:189], v[144:145], 0, v[218:219]
	global_store_dwordx4 v[188:189], v[184:187], off

;     __device__ __forceinline__ void operator()(const f32x4 (&acc)[2][2][4][2], const Unit& u, int wr, int wc, int fr, int fq) const {
;     ...
;                 const int rl = ai * HALF + wr * 64 + m * 16 + fr; const int row = u.pm * BM + rl;
;                 const float rs = rsqrtf(((P[rl * 4 + 0] + P[rl * 4 + 1]) + (P[rl * 4 + 2] + P[rl * 4 + 3])) * invn + EPS);
;                 if (isq) {
; #pragma unroll
;                     for (int bj = 0; bj < 2; ++bj) { const f32x4 g0 = *(const f32x4*)(gq + bj * HALF + c8), g1 = *(const f32x4*)(gq + bj * HALF + c8 + 4);
;                         const f32x4 v0 = acc[ai][bj][m][0] * rs * g0, v1 = acc[ai][bj][m][1] * rs * g1;
;                         u32x4 w; w.x = cvt_pk_bf16(v0[0], v0[1]); w.y = cvt_pk_bf16(v0[2], v0[3]); w.z = cvt_pk_bf16(v1[0], v1[1]); w.w = cvt_pk_bf16(v1[2], v1[3]);
;                         *(u32x4*)(CQNo + (size_t)row * QL + bj * HALF + c8) = w; }
;                 } else {
;                     { const f32x4 g0 = *(const f32x4*)(gkv + c8), g1 = *(const f32x4*)(gkv + c8 + 4);
;                       const f32x4 v0 = acc[ai][0][m][0] * rs * g0, v1 = acc[ai][0][m][1] * rs * g1;
;                       u32x4 w; w.x = cvt_pk_bf16(v0[0], v0[1]); w.y = cvt_pk_bf16(v0[2], v0[3]); w.z = cvt_pk_bf16(v1[0], v1[1]); w.w = cvt_pk_bf16(v1[2], v1[3]);
;                       *(u32x4*)(CKVNo + (size_t)row * KVL + c8) = w; }
;                     if (wc == 0) {
;                         f32x4 v0 = acc[ai][1][m][0], v1 = acc[ai][1][m][1];
;                         const float* rp = rope + (size_t)(row & (SEQ - 1)) * 32 + 16 * (fq & 1);
;                         const f32x4 c0 = *(const f32x4*)rp, c1 = *(const f32x4*)(rp + 4), c2 = *(const f32x4*)(rp + 8), c3 = *(const f32x4*)(rp + 12);
;                         const float cs[8] = {c0[0], c0[2], c1[0], c1[2], c2[0], c2[2], c3[0], c3[2]}, sn[8] = {c0[1], c0[3], c1[1], c1[3], c2[1], c2[3], c3[1], c3[3]};
; #pragma unroll
;                         for (int e = 0; e < 4; ++e) { const float o0 = __shfl_xor(v0[e], 32), o1 = __shfl_xor(v1[e], 32);
;                             v0[e] = v0[e] * cs[e] + sgn * o0 * sn[e]; v1[e] = v1[e] * cs[4 + e] + sgn * o1 * sn[4 + e]; }
;                         u32x4 w; w.x = cvt_pk_bf16(v0[0], v0[1]); w.y = cvt_pk_bf16(v0[2], v0[3]); w.z = cvt_pk_bf16(v1[0], v1[1]); w.w = cvt_pk_bf16(v1[2], v1[3]);
.LBB0_252:
	s_andn2_b64 vcc, exec, s[52:53]
	s_cbranch_vccnz .LBB0_254
	v_lshlrev_b64 v[160:161], 9, v[160:161]
	v_pk_mul_f32 v[192:193], v[62:63], v[158:159] op_sel_hi:[1,0]
	v_pk_mul_f32 v[196:197], v[60:61], v[158:159] op_sel_hi:[1,0]
	v_pk_mul_f32 v[198:199], v[58:59], v[158:159] op_sel_hi:[1,0]
	v_pk_mul_f32 v[200:201], v[56:57], v[158:159] op_sel_hi:[1,0]
	v_lshl_add_u64 v[160:161], v[150:151], 0, v[160:161]
	v_pk_mul_f32 v[186:187], v[192:193], v[222:223]
	v_pk_mul_f32 v[184:185], v[196:197], v[220:221]
	v_pk_mul_f32 v[190:191], v[198:199], v[226:227]
	v_pk_mul_f32 v[188:189], v[200:201], v[224:225]
	v_cvt_pk_bf16_f32 v184, v184, v185
	v_cvt_pk_bf16_f32 v185, v186, v187
	v_pk_mul_f32 v[192:193], v[54:55], v[158:159] op_sel_hi:[1,0]
	v_cvt_pk_bf16_f32 v186, v188, v189
	v_cvt_pk_bf16_f32 v187, v190, v191
	global_store_dwordx4 v[160:161], v[184:187], off
	s_nop 0
	v_pk_mul_f32 v[196:197], v[52:53], v[158:159] op_sel_hi:[1,0]
	v_pk_mul_f32 v[198:199], v[50:51], v[158:159] op_sel_hi:[1,0]
	v_pk_mul_f32 v[200:201], v[48:49], v[158:159] op_sel_hi:[1,0]
	v_pk_mul_f32 v[186:187], v[192:193], v[230:231]
	v_pk_mul_f32 v[184:185], v[196:197], v[228:229]
	v_pk_mul_f32 v[190:191], v[198:199], v[242:243]
	v_pk_mul_f32 v[188:189], v[200:201], v[240:241]
	v_cvt_pk_bf16_f32 v184, v184, v185
	v_cvt_pk_bf16_f32 v185, v186, v187
	s_nop 0
	v_cvt_pk_bf16_f32 v186, v188, v189
	v_cvt_pk_bf16_f32 v187, v190, v191
	global_store_dwordx4 v[160:161], v[184:187], off offset:256
.LBB0_254:
	ds_read_b128 v[184:187], v177
	s_mov_b64 s[52:53], -1
	s_and_b64 vcc, exec, s[10:11]
	s_waitcnt lgkmcnt(0)
	v_mov_b32_e32 v160, v185
	v_mov_b32_e32 v161, v186
	v_mov_b32_e32 v185, v187
	v_pk_add_f32 v[160:161], v[160:161], v[184:185]
	s_nop 0
	v_add_f32_e32 v136, v160, v161
	v_fmaak_f32 v136, v159, v136, 0x358637bd
	v_mul_f32_e32 v158, 0x4b800000, v136
	v_cmp_gt_f32_e64 s[12:13], s68, v136
	v_add_u32_e32 v160, s18, v170
	v_ashrrev_i32_e32 v161, 31, v160
	v_cndmask_b32_e64 v136, v136, v158, s[12:13]
	v_rsq_f32_e32 v136, v136
	s_nop 0
	v_mul_f32_e32 v158, 0x45800000, v136
	v_cndmask_b32_e64 v158, v136, v158, s[12:13]
	s_cbranch_vccnz .LBB0_258
	v_pk_mul_f32 v[192:193], v[46:47], v[158:159] op_sel_hi:[1,0]
	v_pk_mul_f32 v[196:197], v[44:45], v[158:159] op_sel_hi:[1,0]
	v_lshlrev_b64 v[202:203], 8, v[160:161]
	v_pk_mul_f32 v[198:199], v[42:43], v[158:159] op_sel_hi:[1,0]
	v_pk_mul_f32 v[200:201], v[40:41], v[158:159] op_sel_hi:[1,0]
	v_lshl_add_u64 v[202:203], v[140:141], 0, v[202:203]
	s_and_b64 vcc, exec, s[8:9]
	v_pk_mul_f32 v[186:187], v[192:193], v[222:223]
	v_pk_mul_f32 v[184:185], v[196:197], v[220:221]
	v_pk_mul_f32 v[190:191], v[198:199], v[226:227]
	v_pk_mul_f32 v[188:189], v[200:201], v[224:225]
	v_cvt_pk_bf16_f32 v184, v184, v185
	v_cvt_pk_bf16_f32 v185, v186, v187
	s_nop 0
	v_cvt_pk_bf16_f32 v186, v188, v189
	v_cvt_pk_bf16_f32 v187, v190, v191
	global_store_dwordx4 v[202:203], v[184:187], off
	s_cbranch_vccnz .LBB0_257
	v_lshlrev_b32_e32 v136, 7, v160
	v_and_b32_e32 v136, 0x7ef80, v136
	v_lshl_add_u64 v[192:193], v[142:143], 0, v[136:137]
	global_load_dwordx4 v[184:187], v[192:193], off
	global_load_dwordx4 v[188:191], v[192:193], off offset:32
	global_load_dwordx4 v[196:199], v[192:193], off offset:16
	global_load_dwordx4 v[200:203], v[192:193], off offset:48
	ds_bpermute_b32 v136, v183, v36
	ds_bpermute_b32 v182, v183, v32
	ds_bpermute_b32 v207, v183, v37
	ds_bpermute_b32 v209, v183, v33
	ds_bpermute_b32 v211, v183, v38
	ds_bpermute_b32 v213, v183, v34
	ds_bpermute_b32 v215, v183, v39
	ds_bpermute_b32 v217, v183, v35
	v_mov_b32_e32 v192, v36
	v_mov_b32_e32 v204, v32
	v_mov_b32_e32 v206, v37
	v_mov_b32_e32 v208, v33
	v_mov_b32_e32 v210, v38
	v_mov_b32_e32 v212, v34
	v_mov_b32_e32 v214, v39
	v_mov_b32_e32 v216, v35
	s_waitcnt lgkmcnt(7)
	v_mul_f32_e32 v193, v165, v136
	s_waitcnt lgkmcnt(6)
	v_mul_f32_e32 v205, v165, v182
	s_waitcnt lgkmcnt(5)
	v_mul_f32_e32 v207, v165, v207
	s_waitcnt lgkmcnt(4)
	v_mul_f32_e32 v209, v165, v209
	s_waitcnt lgkmcnt(3)
	v_mul_f32_e32 v211, v165, v211
	s_waitcnt lgkmcnt(2)
	v_mul_f32_e32 v213, v165, v213
	s_waitcnt lgkmcnt(1)
	v_mul_f32_e32 v215, v165, v215
	s_waitcnt lgkmcnt(0)
	v_mul_f32_e32 v217, v165, v217
	v_lshlrev_b64 v[218:219], 6, v[160:161]
	s_waitcnt vmcnt(3)
	v_pk_mul_f32 v[184:185], v[184:185], v[192:193]
	s_waitcnt vmcnt(2)
	v_pk_mul_f32 v[188:189], v[188:189], v[204:205]
	v_pk_mul_f32 v[186:187], v[186:187], v[206:207]
	v_pk_mul_f32 v[190:191], v[190:191], v[208:209]
	s_waitcnt vmcnt(1)
	v_pk_mul_f32 v[192:193], v[196:197], v[210:211]
	s_waitcnt vmcnt(0)
	v_pk_mul_f32 v[196:197], v[200:201], v[212:213]
	v_pk_mul_f32 v[198:199], v[198:199], v[214:215]
	v_pk_mul_f32 v[200:201], v[202:203], v[216:217]
	v_add_f32_e32 v136, v184, v185
	v_add_f32_e32 v182, v188, v189
	v_add_f32_e32 v184, v186, v187
	v_add_f32_e32 v186, v190, v191
	v_add_f32_e32 v185, v192, v193
	v_add_f32_e32 v187, v196, v197
	v_add_f32_e32 v188, v198, v199
	v_add_f32_e32 v189, v200, v201
	v_cvt_pk_bf16_f32 v184, v136, v184
	v_cvt_pk_bf16_f32 v185, v185, v188
	v_cvt_pk_bf16_f32 v186, v182, v186
	v_cvt_pk_bf16_f32 v187, v187, v189
	v_lshl_add_u64 v[188:189], v[144:145], 0, v[218:219]
	global_store_dwordx4 v[188:189], v[184:187], off

;     __device__ __forceinline__ void operator()(const f32x4 (&acc)[2][2][4][2], const Unit& u, int wr, int wc, int fr, int fq) const {
;     ...
;                 const int rl = ai * HALF + wr * 64 + m * 16 + fr; const int row = u.pm * BM + rl;
;                 const float rs = rsqrtf(((P[rl * 4 + 0] + P[rl * 4 + 1]) + (P[rl * 4 + 2] + P[rl * 4 + 3])) * invn + EPS);
;                 if (isq) {
; #pragma unroll
;                     for (int bj = 0; bj < 2; ++bj) { const f32x4 g0 = *(const f32x4*)(gq + bj * HALF + c8), g1 = *(const f32x4*)(gq + bj * HALF + c8 + 4);
;                         const f32x4 v0 = acc[ai][bj][m][0] * rs * g0, v1 = acc[ai][bj][m][1] * rs * g1;
;                         u32x4 w; w.x = cvt_pk_bf16(v0[0], v0[1]); w.y = cvt_pk_bf16(v0[2], v0[3]); w.z = cvt_pk_bf16(v1[0], v1[1]); w.w = cvt_pk_bf16(v1[2], v1[3]);
;                         *(u32x4*)(CQNo + (size_t)row * QL + bj * HALF + c8) = w; }
;                 } else {
;                     { const f32x4 g0 = *(const f32x4*)(gkv + c8), g1 = *(const f32x4*)(gkv + c8 + 4);
;                       const f32x4 v0 = acc[ai][0][m][0] * rs * g0, v1 = acc[ai][0][m][1] * rs * g1;
;                       u32x4 w; w.x = cvt_pk_bf16(v0[0], v0[1]); w.y = cvt_pk_bf16(v0[2], v0[3]); w.z = cvt_pk_bf16(v1[0], v1[1]); w.w = cvt_pk_bf16(v1[2], v1[3]);
;                       *(u32x4*)(CKVNo + (size_t)row * KVL + c8) = w; }
;                     if (wc == 0) {
;                         f32x4 v0 = acc[ai][1][m][0], v1 = acc[ai][1][m][1];
;                         const float* rp = rope + (size_t)(row & (SEQ - 1)) * 32 + 16 * (fq & 1);
;                         const f32x4 c0 = *(const f32x4*)rp, c1 = *(const f32x4*)(rp + 4), c2 = *(const f32x4*)(rp + 8), c3 = *(const f32x4*)(rp + 12);
;                         const float cs[8] = {c0[0], c0[2], c1[0], c1[2], c2[0], c2[2], c3[0], c3[2]}, sn[8] = {c0[1], c0[3], c1[1], c1[3], c2[1], c2[3], c3[1], c3[3]};
; #pragma unroll
;                         for (int e = 0; e < 4; ++e) { const float o0 = __shfl_xor(v0[e], 32), o1 = __shfl_xor(v1[e], 32);
;                             v0[e] = v0[e] * cs[e] + sgn * o0 * sn[e]; v1[e] = v1[e] * cs[4 + e] + sgn * o1 * sn[4 + e]; }
;                         u32x4 w; w.x = cvt_pk_bf16(v0[0], v0[1]); w.y = cvt_pk_bf16(v0[2], v0[3]); w.z = cvt_pk_bf16(v1[0], v1[1]); w.w = cvt_pk_bf16(v1[2], v1[3]);
.LBB0_258:
	s_andn2_b64 vcc, exec, s[52:53]
	s_cbranch_vccnz .LBB0_260
	v_lshlrev_b64 v[160:161], 9, v[160:161]
	v_pk_mul_f32 v[192:193], v[46:47], v[158:159] op_sel_hi:[1,0]
	v_pk_mul_f32 v[196:197], v[44:45], v[158:159] op_sel_hi:[1,0]
	v_pk_mul_f32 v[198:199], v[42:43], v[158:159] op_sel_hi:[1,0]
	v_pk_mul_f32 v[200:201], v[40:41], v[158:159] op_sel_hi:[1,0]
	v_lshl_add_u64 v[160:161], v[150:151], 0, v[160:161]
	v_pk_mul_f32 v[186:187], v[192:193], v[222:223]
	v_pk_mul_f32 v[184:185], v[196:197], v[220:221]
	v_pk_mul_f32 v[190:191], v[198:199], v[226:227]
	v_pk_mul_f32 v[188:189], v[200:201], v[224:225]
	v_cvt_pk_bf16_f32 v184, v184, v185
	v_cvt_pk_bf16_f32 v185, v186, v187
	v_pk_mul_f32 v[192:193], v[38:39], v[158:159] op_sel_hi:[1,0]
	v_cvt_pk_bf16_f32 v186, v188, v189
	v_cvt_pk_bf16_f32 v187, v190, v191
	global_store_dwordx4 v[160:161], v[184:187], off
	s_nop 0
	v_pk_mul_f32 v[196:197], v[36:37], v[158:159] op_sel_hi:[1,0]
	v_pk_mul_f32 v[198:199], v[34:35], v[158:159] op_sel_hi:[1,0]
	v_pk_mul_f32 v[200:201], v[32:33], v[158:159] op_sel_hi:[1,0]
	v_pk_mul_f32 v[186:187], v[192:193], v[230:231]
	v_pk_mul_f32 v[184:185], v[196:197], v[228:229]
	v_pk_mul_f32 v[190:191], v[198:199], v[242:243]
	v_pk_mul_f32 v[188:189], v[200:201], v[240:241]
	v_cvt_pk_bf16_f32 v184, v184, v185
	v_cvt_pk_bf16_f32 v185, v186, v187
	s_nop 0
	v_cvt_pk_bf16_f32 v186, v188, v189
	v_cvt_pk_bf16_f32 v187, v190, v191
	global_store_dwordx4 v[160:161], v[184:187], off offset:256
.LBB0_260:
	ds_read_b128 v[184:187], v178
	s_mov_b64 s[52:53], -1
	s_and_b64 vcc, exec, s[10:11]
	s_waitcnt lgkmcnt(0)
	v_mov_b32_e32 v160, v185
	v_mov_b32_e32 v161, v186
	v_mov_b32_e32 v185, v187
	v_pk_add_f32 v[160:161], v[160:161], v[184:185]
	s_nop 0
	v_add_f32_e32 v136, v160, v161
	v_fmaak_f32 v136, v159, v136, 0x358637bd
	v_mul_f32_e32 v158, 0x4b800000, v136
	v_cmp_gt_f32_e64 s[12:13], s68, v136
	v_add_u32_e32 v160, s18, v171
	v_ashrrev_i32_e32 v161, 31, v160
	v_cndmask_b32_e64 v136, v136, v158, s[12:13]
	v_rsq_f32_e32 v136, v136
	s_nop 0
	v_mul_f32_e32 v158, 0x45800000, v136
	v_cndmask_b32_e64 v158, v136, v158, s[12:13]
	s_cbranch_vccnz .LBB0_264
	v_pk_mul_f32 v[192:193], v[30:31], v[158:159] op_sel_hi:[1,0]
	v_pk_mul_f32 v[196:197], v[28:29], v[158:159] op_sel_hi:[1,0]
	v_lshlrev_b64 v[202:203], 8, v[160:161]
	v_pk_mul_f32 v[198:199], v[26:27], v[158:159] op_sel_hi:[1,0]
	v_pk_mul_f32 v[200:201], v[24:25], v[158:159] op_sel_hi:[1,0]
	v_lshl_add_u64 v[202:203], v[140:141], 0, v[202:203]
	s_and_b64 vcc, exec, s[8:9]
	v_pk_mul_f32 v[186:187], v[192:193], v[222:223]
	v_pk_mul_f32 v[184:185], v[196:197], v[220:221]
	v_pk_mul_f32 v[190:191], v[198:199], v[226:227]
	v_pk_mul_f32 v[188:189], v[200:201], v[224:225]
	v_cvt_pk_bf16_f32 v184, v184, v185
	v_cvt_pk_bf16_f32 v185, v186, v187
	s_nop 0
	v_cvt_pk_bf16_f32 v186, v188, v189
	v_cvt_pk_bf16_f32 v187, v190, v191
	global_store_dwordx4 v[202:203], v[184:187], off
	s_cbranch_vccnz .LBB0_263
	v_lshlrev_b32_e32 v136, 7, v160
	v_and_b32_e32 v136, 0x7f780, v136
	v_lshl_add_u64 v[192:193], v[142:143], 0, v[136:137]
	global_load_dwordx4 v[184:187], v[192:193], off
	global_load_dwordx4 v[188:191], v[192:193], off offset:32
	global_load_dwordx4 v[196:199], v[192:193], off offset:16
	global_load_dwordx4 v[200:203], v[192:193], off offset:48
	ds_bpermute_b32 v136, v183, v20
	ds_bpermute_b32 v182, v183, v16
	ds_bpermute_b32 v207, v183, v21
	ds_bpermute_b32 v209, v183, v17
	ds_bpermute_b32 v211, v183, v22
	ds_bpermute_b32 v213, v183, v18
	ds_bpermute_b32 v215, v183, v23
	ds_bpermute_b32 v217, v183, v19
	v_mov_b32_e32 v192, v20
	v_mov_b32_e32 v204, v16
	v_mov_b32_e32 v206, v21
	v_mov_b32_e32 v208, v17
	v_mov_b32_e32 v210, v22
	v_mov_b32_e32 v212, v18
	v_mov_b32_e32 v214, v23
	v_mov_b32_e32 v216, v19
	s_waitcnt lgkmcnt(7)
	v_mul_f32_e32 v193, v165, v136
	s_waitcnt lgkmcnt(6)
	v_mul_f32_e32 v205, v165, v182
	s_waitcnt lgkmcnt(5)
	v_mul_f32_e32 v207, v165, v207
	s_waitcnt lgkmcnt(4)
	v_mul_f32_e32 v209, v165, v209
	s_waitcnt lgkmcnt(3)
	v_mul_f32_e32 v211, v165, v211
	s_waitcnt lgkmcnt(2)
	v_mul_f32_e32 v213, v165, v213
	s_waitcnt lgkmcnt(1)
	v_mul_f32_e32 v215, v165, v215
	s_waitcnt lgkmcnt(0)
	v_mul_f32_e32 v217, v165, v217
	v_lshlrev_b64 v[218:219], 6, v[160:161]
	s_waitcnt vmcnt(3)
	v_pk_mul_f32 v[184:185], v[184:185], v[192:193]
	s_waitcnt vmcnt(2)
	v_pk_mul_f32 v[188:189], v[188:189], v[204:205]
	v_pk_mul_f32 v[186:187], v[186:187], v[206:207]
	v_pk_mul_f32 v[190:191], v[190:191], v[208:209]
	s_waitcnt vmcnt(1)
	v_pk_mul_f32 v[192:193], v[196:197], v[210:211]
	s_waitcnt vmcnt(0)
	v_pk_mul_f32 v[196:197], v[200:201], v[212:213]
	v_pk_mul_f32 v[198:199], v[198:199], v[214:215]
	v_pk_mul_f32 v[200:201], v[202:203], v[216:217]
	v_add_f32_e32 v136, v184, v185
	v_add_f32_e32 v182, v188, v189
	v_add_f32_e32 v184, v186, v187
	v_add_f32_e32 v186, v190, v191
	v_add_f32_e32 v185, v192, v193
	v_add_f32_e32 v187, v196, v197
	v_add_f32_e32 v188, v198, v199
	v_add_f32_e32 v189, v200, v201
	v_cvt_pk_bf16_f32 v184, v136, v184
	v_cvt_pk_bf16_f32 v185, v185, v188
	v_cvt_pk_bf16_f32 v186, v182, v186
	v_cvt_pk_bf16_f32 v187, v187, v189
	v_lshl_add_u64 v[188:189], v[144:145], 0, v[218:219]
	global_store_dwordx4 v[188:189], v[184:187], off

;     __device__ __forceinline__ void operator()(const f32x4 (&acc)[2][2][4][2], const Unit& u, int wr, int wc, int fr, int fq) const {
;     ...
;                 const int rl = ai * HALF + wr * 64 + m * 16 + fr; const int row = u.pm * BM + rl;
;                 const float rs = rsqrtf(((P[rl * 4 + 0] + P[rl * 4 + 1]) + (P[rl * 4 + 2] + P[rl * 4 + 3])) * invn + EPS);
;                 if (isq) {
; #pragma unroll
;                     for (int bj = 0; bj < 2; ++bj) { const f32x4 g0 = *(const f32x4*)(gq + bj * HALF + c8), g1 = *(const f32x4*)(gq + bj * HALF + c8 + 4);
;                         const f32x4 v0 = acc[ai][bj][m][0] * rs * g0, v1 = acc[ai][bj][m][1] * rs * g1;
;                         u32x4 w; w.x = cvt_pk_bf16(v0[0], v0[1]); w.y = cvt_pk_bf16(v0[2], v0[3]); w.z = cvt_pk_bf16(v1[0], v1[1]); w.w = cvt_pk_bf16(v1[2], v1[3]);
;                         *(u32x4*)(CQNo + (size_t)row * QL + bj * HALF + c8) = w; }
;                 } else {
;                     { const f32x4 g0 = *(const f32x4*)(gkv + c8), g1 = *(const f32x4*)(gkv + c8 + 4);
;                       const f32x4 v0 = acc[ai][0][m][0] * rs * g0, v1 = acc[ai][0][m][1] * rs * g1;
;                       u32x4 w; w.x = cvt_pk_bf16(v0[0], v0[1]); w.y = cvt_pk_bf16(v0[2], v0[3]); w.z = cvt_pk_bf16(v1[0], v1[1]); w.w = cvt_pk_bf16(v1[2], v1[3]);
;                       *(u32x4*)(CKVNo + (size_t)row * KVL + c8) = w; }
;                     if (wc == 0) {
;                         f32x4 v0 = acc[ai][1][m][0], v1 = acc[ai][1][m][1];
;                         const float* rp = rope + (size_t)(row & (SEQ - 1)) * 32 + 16 * (fq & 1);
;                         const f32x4 c0 = *(const f32x4*)rp, c1 = *(const f32x4*)(rp + 4), c2 = *(const f32x4*)(rp + 8), c3 = *(const f32x4*)(rp + 12);
;                         const float cs[8] = {c0[0], c0[2], c1[0], c1[2], c2[0], c2[2], c3[0], c3[2]}, sn[8] = {c0[1], c0[3], c1[1], c1[3], c2[1], c2[3], c3[1], c3[3]};
; #pragma unroll
;                         for (int e = 0; e < 4; ++e) { const float o0 = __shfl_xor(v0[e], 32), o1 = __shfl_xor(v1[e], 32);
;                             v0[e] = v0[e] * cs[e] + sgn * o0 * sn[e]; v1[e] = v1[e] * cs[4 + e] + sgn * o1 * sn[4 + e]; }
;                         u32x4 w; w.x = cvt_pk_bf16(v0[0], v0[1]); w.y = cvt_pk_bf16(v0[2], v0[3]); w.z = cvt_pk_bf16(v1[0], v1[1]); w.w = cvt_pk_bf16(v1[2], v1[3]);
.LBB0_264:
	s_andn2_b64 vcc, exec, s[52:53]
	s_cbranch_vccnz .LBB0_266
	v_lshlrev_b64 v[160:161], 9, v[160:161]
	v_pk_mul_f32 v[192:193], v[30:31], v[158:159] op_sel_hi:[1,0]
	v_pk_mul_f32 v[196:197], v[28:29], v[158:159] op_sel_hi:[1,0]
	v_pk_mul_f32 v[198:199], v[26:27], v[158:159] op_sel_hi:[1,0]
	v_pk_mul_f32 v[200:201], v[24:25], v[158:159] op_sel_hi:[1,0]
	v_lshl_add_u64 v[160:161], v[150:151], 0, v[160:161]
	v_pk_mul_f32 v[186:187], v[192:193], v[222:223]
	v_pk_mul_f32 v[184:185], v[196:197], v[220:221]
	v_pk_mul_f32 v[190:191], v[198:199], v[226:227]
	v_pk_mul_f32 v[188:189], v[200:201], v[224:225]
	v_cvt_pk_bf16_f32 v184, v184, v185
	v_cvt_pk_bf16_f32 v185, v186, v187
	v_pk_mul_f32 v[192:193], v[22:23], v[158:159] op_sel_hi:[1,0]
	v_cvt_pk_bf16_f32 v186, v188, v189
	v_cvt_pk_bf16_f32 v187, v190, v191
	global_store_dwordx4 v[160:161], v[184:187], off
	s_nop 0
	v_pk_mul_f32 v[196:197], v[20:21], v[158:159] op_sel_hi:[1,0]
	v_pk_mul_f32 v[198:199], v[18:19], v[158:159] op_sel_hi:[1,0]
	v_pk_mul_f32 v[200:201], v[16:17], v[158:159] op_sel_hi:[1,0]
	v_pk_mul_f32 v[186:187], v[192:193], v[230:231]
	v_pk_mul_f32 v[184:185], v[196:197], v[228:229]
	v_pk_mul_f32 v[190:191], v[198:199], v[242:243]
	v_pk_mul_f32 v[188:189], v[200:201], v[240:241]
	v_cvt_pk_bf16_f32 v184, v184, v185
	v_cvt_pk_bf16_f32 v185, v186, v187
	s_nop 0
	v_cvt_pk_bf16_f32 v186, v188, v189
	v_cvt_pk_bf16_f32 v187, v190, v191
	global_store_dwordx4 v[160:161], v[184:187], off offset:256
.LBB0_266:
	ds_read_b128 v[184:187], v179
	s_mov_b64 s[52:53], -1
	s_and_b64 vcc, exec, s[10:11]
	s_waitcnt lgkmcnt(0)
	v_mov_b32_e32 v160, v185
	v_mov_b32_e32 v161, v186
	v_mov_b32_e32 v185, v187
	v_pk_add_f32 v[160:161], v[160:161], v[184:185]
	s_nop 0
	v_add_f32_e32 v136, v160, v161
	v_fmaak_f32 v136, v159, v136, 0x358637bd
	v_mul_f32_e32 v158, 0x4b800000, v136
	v_cmp_gt_f32_e64 s[12:13], s68, v136
	v_add_u32_e32 v160, s18, v172
	v_ashrrev_i32_e32 v161, 31, v160
	v_cndmask_b32_e64 v136, v136, v158, s[12:13]
	v_rsq_f32_e32 v136, v136
	s_nop 0
	v_mul_f32_e32 v158, 0x45800000, v136
	v_cndmask_b32_e64 v158, v136, v158, s[12:13]
	s_cbranch_vccnz .LBB0_270
	v_pk_mul_f32 v[192:193], v[14:15], v[158:159] op_sel_hi:[1,0]
	v_pk_mul_f32 v[196:197], v[12:13], v[158:159] op_sel_hi:[1,0]
	v_lshlrev_b64 v[202:203], 8, v[160:161]
	v_pk_mul_f32 v[198:199], v[10:11], v[158:159] op_sel_hi:[1,0]
	v_pk_mul_f32 v[200:201], v[8:9], v[158:159] op_sel_hi:[1,0]
	v_lshl_add_u64 v[202:203], v[140:141], 0, v[202:203]
	s_and_b64 vcc, exec, s[8:9]
	v_pk_mul_f32 v[186:187], v[192:193], v[222:223]
	v_pk_mul_f32 v[184:185], v[196:197], v[220:221]
	v_pk_mul_f32 v[190:191], v[198:199], v[226:227]
	v_pk_mul_f32 v[188:189], v[200:201], v[224:225]
	v_cvt_pk_bf16_f32 v184, v184, v185
	v_cvt_pk_bf16_f32 v185, v186, v187
	s_nop 0
	v_cvt_pk_bf16_f32 v186, v188, v189
	v_cvt_pk_bf16_f32 v187, v190, v191
	global_store_dwordx4 v[202:203], v[184:187], off
	s_cbranch_vccnz .LBB0_269
	v_lshlrev_b32_e32 v136, 7, v160
	v_and_b32_e32 v136, 0x7ff80, v136
	v_lshl_add_u64 v[192:193], v[142:143], 0, v[136:137]
	global_load_dwordx4 v[184:187], v[192:193], off
	global_load_dwordx4 v[188:191], v[192:193], off offset:32
	global_load_dwordx4 v[196:199], v[192:193], off offset:16
	global_load_dwordx4 v[200:203], v[192:193], off offset:48
	ds_bpermute_b32 v136, v183, v4
	ds_bpermute_b32 v159, v183, v0
	ds_bpermute_b32 v205, v183, v5
	ds_bpermute_b32 v207, v183, v1
	ds_bpermute_b32 v209, v183, v6
	ds_bpermute_b32 v213, v183, v7
	ds_bpermute_b32 v211, v183, v2
	ds_bpermute_b32 v215, v183, v3
	v_mov_b32_e32 v182, v4
	v_mov_b32_e32 v192, v0
	v_mov_b32_e32 v204, v5
	v_mov_b32_e32 v206, v1
	v_mov_b32_e32 v208, v6
	v_mov_b32_e32 v212, v7
	s_waitcnt lgkmcnt(7)
	v_mul_f32_e32 v183, v165, v136
	s_waitcnt lgkmcnt(6)
	v_mul_f32_e32 v193, v165, v159
	s_waitcnt lgkmcnt(5)
	v_mul_f32_e32 v205, v165, v205
	s_waitcnt lgkmcnt(4)
	v_mul_f32_e32 v207, v165, v207
	s_waitcnt lgkmcnt(3)
	v_mul_f32_e32 v209, v165, v209
	s_waitcnt lgkmcnt(2)
	v_mul_f32_e32 v213, v165, v213
	v_mov_b32_e32 v210, v2
	s_waitcnt lgkmcnt(1)
	v_mul_f32_e32 v211, v165, v211
	v_mov_b32_e32 v214, v3
	v_lshlrev_b64 v[216:217], 6, v[160:161]
	s_waitcnt lgkmcnt(0)
	v_mul_f32_e32 v215, v165, v215
	s_waitcnt vmcnt(3)
	v_pk_mul_f32 v[182:183], v[184:185], v[182:183]
	s_waitcnt vmcnt(2)
	v_pk_mul_f32 v[184:185], v[188:189], v[192:193]
	v_pk_mul_f32 v[186:187], v[186:187], v[204:205]
	v_pk_mul_f32 v[188:189], v[190:191], v[206:207]
	s_waitcnt vmcnt(1)
	v_pk_mul_f32 v[190:191], v[196:197], v[208:209]
	v_pk_mul_f32 v[196:197], v[198:199], v[212:213]
	s_waitcnt vmcnt(0)
	v_pk_mul_f32 v[192:193], v[200:201], v[210:211]
	v_add_f32_e32 v136, v182, v183
	v_add_f32_e32 v159, v184, v185
	v_add_f32_e32 v182, v186, v187
	v_add_f32_e32 v183, v188, v189
	v_add_f32_e32 v185, v190, v191
	v_add_f32_e32 v186, v196, v197
	v_pk_mul_f32 v[198:199], v[202:203], v[214:215]
	v_add_f32_e32 v187, v192, v193
	v_cvt_pk_bf16_f32 v184, v136, v182
	v_cvt_pk_bf16_f32 v185, v185, v186
	v_cvt_pk_bf16_f32 v186, v159, v183
	v_lshl_add_u64 v[182:183], v[144:145], 0, v[216:217]
	v_add_f32_e32 v188, v198, v199
	v_cvt_pk_bf16_f32 v187, v187, v188
	global_store_dwordx4 v[182:183], v[184:187], off

; __device__ __forceinline__ unsigned cvt_pk_bf16(float lo, float hi) { unsigned r; asm volatile("v_cvt_pk_bf16_f32 %0, %1, %2" : "=v"(r) : "v"(lo), "v"(hi)); return r; }
;     __device__ __forceinline__ void operator()(const f32x4 (&acc)[2][2][4][2], const Unit& u, int wr, int wc, int fr, int fq) const {
;     ...
;                 const int rl = ai * HALF + wr * 64 + m * 16 + fr; const int row = u.pm * BM + rl;
;                 const float rs = rsqrtf(((P[rl * 4 + 0] + P[rl * 4 + 1]) + (P[rl * 4 + 2] + P[rl * 4 + 3])) * invn + EPS);
;                 if (isq) {
; #pragma unroll
;                     for (int bj = 0; bj < 2; ++bj) { const f32x4 g0 = *(const f32x4*)(gq + bj * HALF + c8), g1 = *(const f32x4*)(gq + bj * HALF + c8 + 4);
;                         const f32x4 v0 = acc[ai][bj][m][0] * rs * g0, v1 = acc[ai][bj][m][1] * rs * g1;
;                         u32x4 w; w.x = cvt_pk_bf16(v0[0], v0[1]); w.y = cvt_pk_bf16(v0[2], v0[3]); w.z = cvt_pk_bf16(v1[0], v1[1]); w.w = cvt_pk_bf16(v1[2], v1[3]);
;                         *(u32x4*)(CQNo + (size_t)row * QL + bj * HALF + c8) = w; }
.LBB0_270:
	s_andn2_b64 vcc, exec, s[52:53]
	s_cbranch_vccnz .LBB0_272
	v_lshlrev_b64 v[160:161], 9, v[160:161]
	v_pk_mul_f32 v[182:183], v[14:15], v[158:159] op_sel_hi:[1,0]
	v_pk_mul_f32 v[198:199], v[8:9], v[158:159] op_sel_hi:[1,0]
	v_pk_mul_f32 v[192:193], v[12:13], v[158:159] op_sel_hi:[1,0]
	v_pk_mul_f32 v[196:197], v[10:11], v[158:159] op_sel_hi:[1,0]
	v_lshl_add_u64 v[200:201], v[150:151], 0, v[160:161]
	v_pk_mul_f32 v[160:161], v[182:183], v[222:223]
	v_pk_mul_f32 v[186:187], v[198:199], v[224:225]
	v_pk_mul_f32 v[182:183], v[192:193], v[220:221]
	v_pk_mul_f32 v[190:191], v[196:197], v[226:227]
	v_cvt_pk_bf16_f32 v184, v182, v183
	v_cvt_pk_bf16_f32 v185, v160, v161
	v_cvt_pk_bf16_f32 v186, v186, v187
	v_pk_mul_f32 v[160:161], v[6:7], v[158:159] op_sel_hi:[1,0]
	v_cvt_pk_bf16_f32 v187, v190, v191
	global_store_dwordx4 v[200:201], v[184:187], off
	s_nop 0
	v_pk_mul_f32 v[182:183], v[4:5], v[158:159] op_sel_hi:[1,0]
	v_pk_mul_f32 v[192:193], v[2:3], v[158:159] op_sel_hi:[1,0]
	v_pk_mul_f32 v[158:159], v[0:1], v[158:159] op_sel_hi:[1,0]
	v_pk_mul_f32 v[160:161], v[160:161], v[230:231]
	v_pk_mul_f32 v[182:183], v[182:183], v[228:229]
	v_pk_mul_f32 v[184:185], v[192:193], v[242:243]
	v_pk_mul_f32 v[186:187], v[158:159], v[240:241]
	v_cvt_pk_bf16_f32 v158, v182, v183
	v_cvt_pk_bf16_f32 v159, v160, v161
	s_nop 0
	v_cvt_pk_bf16_f32 v160, v186, v187
	v_cvt_pk_bf16_f32 v161, v184, v185
	global_store_dwordx4 v[200:201], v[158:161], off offset:256
